# attention w_o GEMM phase: the four workgroup groups start 0/2/4/6 us apart (de-phases their epilogue bursts, as the Fourier w_o GEMM already does)
# speedup vs baseline: 1.0032x; 1.0001x over previous
.LBB0_850:
	s_cmp_lt_i32 s56, 13
	s_cselect_b64 s[0:1], -1, 0
	s_and_b64 s[8:9], s[0:1], s[4:5]
	s_andn2_b64 vcc, exec, s[8:9]
	s_cbranch_vccnz .LBB0_889
	s_bfe_u32 s0, s2, 0x20003
	s_cmp_eq_u32 s0, 0
	s_cbranch_scc1 .Lwo_nostag
	s_mul_i32 s0, s0, 1

.Lwo_nostag:
	s_cmpk_lt_i32 s2, 0x200
	s_cselect_b64 s[4:5], -1, 0
	s_cmpk_gt_i32 s2, 0x1ff
	v_readfirstlane_b32 s6, v197
	v_mbcnt_lo_u32_b32 v0, -1, 0
	v_mbcnt_hi_u32_b32 v0, -1, v0
	s_cbranch_scc1 .LBB0_853
	v_readlane_b32 s0, v248, 5
	v_readlane_b32 s1, v248, 6
	s_and_b64 s[0:1], s[0:1], exec
	v_readlane_b32 s0, v248, 7
	v_readlane_b32 s1, v248, 8
	s_cselect_b32 s0, s1, s0
	s_add_i32 s0, s0, s92
	s_ashr_i32 s1, s0, 31
	s_lshr_b32 s1, s1, 26
	s_add_i32 s1, s0, s1
	s_ashr_i32 s7, s1, 6
	s_and_b32 s1, s1, 0xffc0
	s_sub_i32 s0, s0, s1
	s_bfe_i32 s1, s0, 0x80000
	s_bfe_u32 s1, s1, 0x3000c
	s_add_i32 s1, s0, s1
	s_bfe_i32 s10, s1, 0x80000
	s_and_b32 s1, s1, 0xf8
	s_sub_i32 s0, s0, s1
	s_lshl_b32 s7, s7, 3
	s_sext_i32_i16 s10, s10
	s_sext_i32_i8 s0, s0
	s_add_i32 s30, s7, s0
	s_ashr_i32 s28, s10, 3
